# v41 + SwiGLU epilogue (dead rsqrtf denormal arm removed, permlane reduction) + MLA deferred adds under the LDS read latency
# baseline (speedup 1.0000x reference)
; __device__ __forceinline__ unsigned cvt_pk_bf16(float lo, float hi) { unsigned r; asm volatile("v_cvt_pk_bf16_f32 %0, %1, %2" : "=v"(r) : "v"(lo), "v"(hi)); return r; }
; __device__ __forceinline__ float rstd_from(const float* ps, int row, int off4, int n4, float inv_dim, int fq) {
;     float s = 0.f;
;     if (fq < n4) { const f32x4 v = *((const f32x4*)(ps + (size_t)row * 16) + off4 + fq); s = (v[0] + v[1]) + (v[2] + v[3]); }
;     s += __shfl_xor(s, 16); s += __shfl_xor(s, 32);
;     return rsqrtf(s * inv_dim + 1e-6f);
; }
;     __device__ __forceinline__ void operator()(const f32x4 (&acc)[2][2][4][2], const Unit& u, int wr, int wc, int fr, int fq) const {
;         const int row0 = u.pm * BM + wr * 64 + fr, col0 = u.pn * 128 + wc * 32 + 8 * fq;
; #pragma unroll
;         for (int ai = 0; ai < 2; ++ai)
; #pragma unroll
;             for (int m = 0; m < 4; ++m) {
;                 const int row = row0 + ai * HALF + m * 16;
;                 const float rs = rstd_from(ps, row, 0, 4, 1.f / 1024.f, fq);
;                 float hv[8];
; #pragma unroll
;                 for (int n = 0; n < 2; ++n)
; #pragma unroll
;                     for (int e = 0; e < 4; ++e) { const float gt = acc[ai][0][m][n][e] * rs, up = acc[ai][1][m][n][e] * rs;
;                         hv[n * 4 + e] = gt * __builtin_amdgcn_rcpf(1.f + __builtin_amdgcn_exp2f(-1.4426950408889634f * gt)) * up; }
;                 u32x4 w; w.x = cvt_pk_bf16(hv[0], hv[1]); w.y = cvt_pk_bf16(hv[2], hv[3]); w.z = cvt_pk_bf16(hv[4], hv[5]); w.w = cvt_pk_bf16(hv[6], hv[7]);
;                 *(u32x4*)(H + (size_t)row * 2816 + col0) = w;
.LBB0_1171:
	v_and_b32_e32 v143, 64, v204
	v_xor_b32_e32 v141, 16, v204
	v_add_u32_e32 v143, 64, v143
	v_cmp_lt_i32_e32 vcc, v141, v143
	v_lshl_add_u32 v140, s7, 8, v145
	v_lshl_or_b32 v142, s2, 7, v147
	v_cndmask_b32_e32 v141, v204, v141, vcc
	v_lshlrev_b32_e32 v149, 2, v141
	v_xor_b32_e32 v141, 32, v204
	v_cmp_lt_i32_e32 vcc, v141, v143
	v_ashrrev_i32_e32 v143, 31, v142
	s_movk_i32 s4, 0x2000
	v_cndmask_b32_e32 v141, v204, v141, vcc
	v_lshlrev_b32_e32 v150, 2, v141
	v_ashrrev_i32_e32 v141, 31, v140
	v_lshlrev_b64 v[152:153], 6, v[140:141]
	s_mov_b32 s5, 0
	v_lshl_add_u64 v[152:153], v[134:135], 0, v[152:153]
	v_lshl_add_u64 v[154:155], v[152:153], 0, s[4:5]
	global_load_dwordx4 v[156:159], v[152:153], off
	global_load_dwordx4 v[160:163], v[152:153], off offset:1024
	global_load_dwordx4 v[164:167], v[152:153], off offset:2048
	global_load_dwordx4 v[172:175], v[152:153], off offset:3072
	global_load_dwordx4 v[176:179], v[154:155], off
	global_load_dwordx4 v[180:183], v[154:155], off offset:1024
	global_load_dwordx4 v[184:187], v[154:155], off offset:2048
	global_load_dwordx4 v[188:191], v[154:155], off offset:3072
	v_mov_b64_e32 v[236:237], s[26:27]
	v_lshlrev_b64 v[238:239], 1, v[142:143]
	v_mad_i64_i32 v[234:235], s[4:5], v140, s17, v[236:237]
	s_lshl_b32 s4, s17, 4
	s_mov_b32 s5, 0
	v_lshl_add_u64 v[234:235], v[234:235], 0, v[238:239]
	v_lshl_add_u64 v[236:237], s[4:5], 0, v[234:235]
	v_lshl_add_u64 v[238:239], s[4:5], 1, v[234:235]
	v_lshl_add_u64 v[240:241], s[4:5], 1, v[236:237]
	s_waitcnt vmcnt(7)
	v_add_f32_e32 v156, v157, v156
	v_add_f32_e32 v158, v158, v159
	s_waitcnt vmcnt(6)
	v_add_f32_e32 v160, v161, v160
	v_add_f32_e32 v162, v162, v163
	s_waitcnt vmcnt(5)
	v_add_f32_e32 v164, v165, v164
	v_add_f32_e32 v166, v166, v167
	s_waitcnt vmcnt(4)
	v_add_f32_e32 v172, v173, v172
	v_add_f32_e32 v174, v174, v175
	s_waitcnt vmcnt(3)
	v_add_f32_e32 v176, v177, v176
	v_add_f32_e32 v178, v178, v179
	s_waitcnt vmcnt(2)
	v_add_f32_e32 v180, v181, v180
	v_add_f32_e32 v182, v182, v183
	s_waitcnt vmcnt(1)
	v_add_f32_e32 v184, v185, v184
	v_add_f32_e32 v186, v186, v187
	s_waitcnt vmcnt(0)
	v_add_f32_e32 v188, v189, v188
	v_add_f32_e32 v190, v190, v191
	v_add_f32_e32 v156, v156, v158
	v_add_f32_e32 v160, v160, v162
	v_add_f32_e32 v164, v164, v166
	v_add_f32_e32 v172, v172, v174
	v_add_f32_e32 v176, v176, v178
	v_add_f32_e32 v180, v180, v182
	v_add_f32_e32 v184, v184, v186
	v_add_f32_e32 v188, v188, v190
	v_mov_b32_e32 v157, v156
	v_mov_b32_e32 v161, v160
	v_mov_b32_e32 v165, v164
	v_mov_b32_e32 v173, v172
	v_mov_b32_e32 v177, v176
	v_mov_b32_e32 v181, v180
	v_mov_b32_e32 v185, v184
	v_mov_b32_e32 v189, v188
	v_permlane16_swap_b32_e32 v156, v157
	v_permlane16_swap_b32_e32 v160, v161
	v_permlane16_swap_b32_e32 v164, v165
	v_permlane16_swap_b32_e32 v172, v173
	v_permlane16_swap_b32_e32 v176, v177
	v_permlane16_swap_b32_e32 v180, v181
	v_permlane16_swap_b32_e32 v184, v185
	v_permlane16_swap_b32_e32 v188, v189
	v_add_f32_e32 v156, v156, v157
	v_add_f32_e32 v160, v160, v161
	v_add_f32_e32 v164, v164, v165
	v_add_f32_e32 v172, v172, v173
	v_add_f32_e32 v176, v176, v177
	v_add_f32_e32 v180, v180, v181
	v_add_f32_e32 v184, v184, v185
	v_add_f32_e32 v188, v188, v189
	v_mov_b32_e32 v157, v156
	v_mov_b32_e32 v161, v160
	v_mov_b32_e32 v165, v164
	v_mov_b32_e32 v173, v172
	v_mov_b32_e32 v177, v176
	v_mov_b32_e32 v181, v180
	v_mov_b32_e32 v185, v184
	v_mov_b32_e32 v189, v188
	v_permlane32_swap_b32_e32 v156, v157
	v_permlane32_swap_b32_e32 v160, v161
	v_permlane32_swap_b32_e32 v164, v165
	v_permlane32_swap_b32_e32 v172, v173
	v_permlane32_swap_b32_e32 v176, v177
	v_permlane32_swap_b32_e32 v180, v181
	v_permlane32_swap_b32_e32 v184, v185
	v_permlane32_swap_b32_e32 v188, v189
	v_add_f32_e32 v156, v156, v157
	v_add_f32_e32 v160, v160, v161
	v_add_f32_e32 v164, v164, v165
	v_add_f32_e32 v172, v172, v173
	v_add_f32_e32 v176, v176, v177
	v_add_f32_e32 v180, v180, v181
	v_add_f32_e32 v184, v184, v185
	v_add_f32_e32 v188, v188, v189
	v_fmamk_f32 v156, v156, 0x3a800000, v202
	v_fmamk_f32 v160, v160, 0x3a800000, v202
	v_fmamk_f32 v164, v164, 0x3a800000, v202
	v_fmamk_f32 v172, v172, 0x3a800000, v202
	v_fmamk_f32 v176, v176, 0x3a800000, v202
	v_fmamk_f32 v180, v180, 0x3a800000, v202
	v_fmamk_f32 v184, v184, 0x3a800000, v202
	v_fmamk_f32 v188, v188, 0x3a800000, v202
	v_rsq_f32_e32 v158, v156
	v_rsq_f32_e32 v162, v160
	v_rsq_f32_e32 v166, v164
	v_rsq_f32_e32 v174, v172
	v_rsq_f32_e32 v178, v176
	v_rsq_f32_e32 v182, v180
	v_rsq_f32_e32 v186, v184
	v_rsq_f32_e32 v190, v188
	s_lshl_b32 s4, s17, 4
	s_mov_b32 s5, 0
	v_mul_f32_e32 v120, v120, v158
	v_mul_f32_e32 v121, v121, v158
	v_mul_f32_e32 v122, v122, v158
	v_mul_f32_e32 v123, v123, v158
	v_mul_f32_e32 v112, v112, v158
	v_mul_f32_e32 v113, v113, v158
	v_mul_f32_e32 v114, v114, v158
	v_mul_f32_e32 v115, v115, v158
	v_mul_f32_e32 v218, 0xbfb8aa3b, v120
	v_mul_f32_e32 v219, 0xbfb8aa3b, v121
	v_mul_f32_e32 v220, 0xbfb8aa3b, v122
	v_mul_f32_e32 v221, 0xbfb8aa3b, v123
	v_mul_f32_e32 v222, 0xbfb8aa3b, v112
	v_mul_f32_e32 v223, 0xbfb8aa3b, v113
	v_mul_f32_e32 v224, 0xbfb8aa3b, v114
	v_mul_f32_e32 v225, 0xbfb8aa3b, v115
	v_exp_f32_e32 v218, v218
	v_exp_f32_e32 v219, v219
	v_exp_f32_e32 v220, v220
	v_exp_f32_e32 v221, v221
	v_exp_f32_e32 v222, v222
	v_exp_f32_e32 v223, v223
	v_exp_f32_e32 v224, v224
	v_exp_f32_e32 v225, v225
	v_add_f32_e32 v218, 1.0, v218
	v_add_f32_e32 v219, 1.0, v219
	v_add_f32_e32 v220, 1.0, v220
	v_add_f32_e32 v221, 1.0, v221
	v_add_f32_e32 v222, 1.0, v222
	v_add_f32_e32 v223, 1.0, v223
	v_add_f32_e32 v224, 1.0, v224
	v_add_f32_e32 v225, 1.0, v225
	v_rcp_f32_e32 v218, v218
	v_rcp_f32_e32 v219, v219
	v_rcp_f32_e32 v220, v220
; __device__ __forceinline__ unsigned cvt_pk_bf16(float lo, float hi) { unsigned r; asm volatile("v_cvt_pk_bf16_f32 %0, %1, %2" : "=v"(r) : "v"(lo), "v"(hi)); return r; }
;     __device__ __forceinline__ void operator()(const f32x4 (&acc)[2][2][4][2], const Unit& u, int wr, int wc, int fr, int fq) const {
;     ...
;                     for (int e = 0; e < 4; ++e) { const float gt = acc[ai][0][m][n][e] * rs, up = acc[ai][1][m][n][e] * rs;
;                         hv[n * 4 + e] = gt * __builtin_amdgcn_rcpf(1.f + __builtin_amdgcn_exp2f(-1.4426950408889634f * gt)) * up; }
;                 u32x4 w; w.x = cvt_pk_bf16(hv[0], hv[1]); w.y = cvt_pk_bf16(hv[2], hv[3]); w.z = cvt_pk_bf16(hv[4], hv[5]); w.w = cvt_pk_bf16(hv[6], hv[7]);
;                 *(u32x4*)(H + (size_t)row * 2816 + col0) = w;
	v_rcp_f32_e32 v221, v221
	v_rcp_f32_e32 v222, v222
	v_rcp_f32_e32 v223, v223
	v_rcp_f32_e32 v224, v224
	v_rcp_f32_e32 v225, v225
	v_mul_f32_e32 v218, v120, v218
	v_mul_f32_e32 v219, v121, v219
	v_mul_f32_e32 v220, v122, v220
	v_mul_f32_e32 v221, v123, v221
	v_mul_f32_e32 v222, v112, v222
	v_mul_f32_e32 v223, v113, v223
	v_mul_f32_e32 v224, v114, v224
	v_mul_f32_e32 v225, v115, v225
	v_mul_f32_e32 v124, v124, v158
	v_mul_f32_e32 v125, v125, v158
	v_mul_f32_e32 v126, v126, v158
	v_mul_f32_e32 v127, v127, v158
	v_mul_f32_e32 v116, v116, v158
	v_mul_f32_e32 v117, v117, v158
	v_mul_f32_e32 v118, v118, v158
	v_mul_f32_e32 v119, v119, v158
	v_mul_f32_e32 v124, v124, v218
	v_mul_f32_e32 v125, v125, v219
	v_mul_f32_e32 v126, v126, v220
	v_mul_f32_e32 v127, v127, v221
	v_mul_f32_e32 v116, v116, v222
	v_mul_f32_e32 v117, v117, v223
	v_mul_f32_e32 v118, v118, v224
	v_mul_f32_e32 v119, v119, v225
	v_cvt_pk_bf16_f32 v226, v124, v125
	v_cvt_pk_bf16_f32 v227, v126, v127
	v_cvt_pk_bf16_f32 v228, v116, v117
	v_cvt_pk_bf16_f32 v229, v118, v119
	global_store_dwordx4 v[234:235], v[226:229], off
	v_mul_f32_e32 v104, v104, v162
	v_mul_f32_e32 v105, v105, v162
	v_mul_f32_e32 v106, v106, v162
	v_mul_f32_e32 v107, v107, v162
	v_mul_f32_e32 v96, v96, v162
	v_mul_f32_e32 v97, v97, v162
	v_mul_f32_e32 v98, v98, v162
	v_mul_f32_e32 v99, v99, v162
	v_mul_f32_e32 v218, 0xbfb8aa3b, v104
	v_mul_f32_e32 v219, 0xbfb8aa3b, v105
	v_mul_f32_e32 v220, 0xbfb8aa3b, v106
	v_mul_f32_e32 v221, 0xbfb8aa3b, v107
	v_mul_f32_e32 v222, 0xbfb8aa3b, v96
	v_mul_f32_e32 v223, 0xbfb8aa3b, v97
	v_mul_f32_e32 v224, 0xbfb8aa3b, v98
	v_mul_f32_e32 v225, 0xbfb8aa3b, v99
	v_exp_f32_e32 v218, v218
	v_exp_f32_e32 v219, v219
	v_exp_f32_e32 v220, v220
	v_exp_f32_e32 v221, v221
	v_exp_f32_e32 v222, v222
	v_exp_f32_e32 v223, v223
	v_exp_f32_e32 v224, v224
	v_exp_f32_e32 v225, v225
	v_add_f32_e32 v218, 1.0, v218
	v_add_f32_e32 v219, 1.0, v219
	v_add_f32_e32 v220, 1.0, v220
	v_add_f32_e32 v221, 1.0, v221
	v_add_f32_e32 v222, 1.0, v222
	v_add_f32_e32 v223, 1.0, v223
	v_add_f32_e32 v224, 1.0, v224
	v_add_f32_e32 v225, 1.0, v225
	v_rcp_f32_e32 v218, v218
	v_rcp_f32_e32 v219, v219
	v_rcp_f32_e32 v220, v220
	v_rcp_f32_e32 v221, v221
	v_rcp_f32_e32 v222, v222
	v_rcp_f32_e32 v223, v223
	v_rcp_f32_e32 v224, v224
	v_rcp_f32_e32 v225, v225
	v_mul_f32_e32 v218, v104, v218
	v_mul_f32_e32 v219, v105, v219
	v_mul_f32_e32 v220, v106, v220
	v_mul_f32_e32 v221, v107, v221
	v_mul_f32_e32 v222, v96, v222
	v_mul_f32_e32 v223, v97, v223
	v_mul_f32_e32 v224, v98, v224
	v_mul_f32_e32 v225, v99, v225
	v_mul_f32_e32 v108, v108, v162
	v_mul_f32_e32 v109, v109, v162
	v_mul_f32_e32 v110, v110, v162
	v_mul_f32_e32 v111, v111, v162
	v_mul_f32_e32 v100, v100, v162
	v_mul_f32_e32 v101, v101, v162
	v_mul_f32_e32 v102, v102, v162
	v_mul_f32_e32 v103, v103, v162
	v_mul_f32_e32 v108, v108, v218
	v_mul_f32_e32 v109, v109, v219
	v_mul_f32_e32 v110, v110, v220
	v_mul_f32_e32 v111, v111, v221
	v_mul_f32_e32 v100, v100, v222
	v_mul_f32_e32 v101, v101, v223
	v_mul_f32_e32 v102, v102, v224
	v_mul_f32_e32 v103, v103, v225
	v_cvt_pk_bf16_f32 v230, v108, v109
	v_cvt_pk_bf16_f32 v231, v110, v111
	v_cvt_pk_bf16_f32 v232, v100, v101
	v_cvt_pk_bf16_f32 v233, v102, v103
	global_store_dwordx4 v[236:237], v[230:233], off
	v_mul_f32_e32 v88, v88, v166
	v_mul_f32_e32 v89, v89, v166
	v_mul_f32_e32 v90, v90, v166
	v_mul_f32_e32 v91, v91, v166
	v_mul_f32_e32 v80, v80, v166
	v_mul_f32_e32 v81, v81, v166
	v_mul_f32_e32 v82, v82, v166
	v_mul_f32_e32 v83, v83, v166
	v_mul_f32_e32 v218, 0xbfb8aa3b, v88
	v_mul_f32_e32 v219, 0xbfb8aa3b, v89
	v_mul_f32_e32 v220, 0xbfb8aa3b, v90
	v_mul_f32_e32 v221, 0xbfb8aa3b, v91
	v_mul_f32_e32 v222, 0xbfb8aa3b, v80
	v_mul_f32_e32 v223, 0xbfb8aa3b, v81
	v_mul_f32_e32 v224, 0xbfb8aa3b, v82
	v_mul_f32_e32 v225, 0xbfb8aa3b, v83
	v_exp_f32_e32 v218, v218
	v_exp_f32_e32 v219, v219
	v_exp_f32_e32 v220, v220
	v_exp_f32_e32 v221, v221
	v_exp_f32_e32 v222, v222
	v_exp_f32_e32 v223, v223
	v_exp_f32_e32 v224, v224
	v_exp_f32_e32 v225, v225
	v_add_f32_e32 v218, 1.0, v218
	v_add_f32_e32 v219, 1.0, v219
	v_add_f32_e32 v220, 1.0, v220
	v_add_f32_e32 v221, 1.0, v221
	v_add_f32_e32 v222, 1.0, v222
	v_add_f32_e32 v223, 1.0, v223
	v_add_f32_e32 v224, 1.0, v224
	v_add_f32_e32 v225, 1.0, v225
	v_rcp_f32_e32 v218, v218
	v_rcp_f32_e32 v219, v219
	v_rcp_f32_e32 v220, v220
	v_rcp_f32_e32 v221, v221
	v_rcp_f32_e32 v222, v222
	v_rcp_f32_e32 v223, v223
	v_rcp_f32_e32 v224, v224
	v_rcp_f32_e32 v225, v225
	v_mul_f32_e32 v218, v88, v218
	v_mul_f32_e32 v219, v89, v219
	v_mul_f32_e32 v220, v90, v220
	v_mul_f32_e32 v221, v91, v221
	v_mul_f32_e32 v222, v80, v222
	v_mul_f32_e32 v223, v81, v223
	v_mul_f32_e32 v224, v82, v224
	v_mul_f32_e32 v225, v83, v225
	v_mul_f32_e32 v92, v92, v166
	v_mul_f32_e32 v93, v93, v166
	v_mul_f32_e32 v94, v94, v166
	v_mul_f32_e32 v95, v95, v166
	v_mul_f32_e32 v84, v84, v166
	v_mul_f32_e32 v85, v85, v166
	v_mul_f32_e32 v86, v86, v166
	v_mul_f32_e32 v87, v87, v166
	v_mul_f32_e32 v92, v92, v218
	v_mul_f32_e32 v93, v93, v219
	v_mul_f32_e32 v94, v94, v220
	v_mul_f32_e32 v95, v95, v221
	v_mul_f32_e32 v84, v84, v222
	v_mul_f32_e32 v85, v85, v223
	v_mul_f32_e32 v86, v86, v224
	v_mul_f32_e32 v87, v87, v225
	v_cvt_pk_bf16_f32 v226, v92, v93
	v_cvt_pk_bf16_f32 v227, v94, v95
	v_cvt_pk_bf16_f32 v228, v84, v85
	v_cvt_pk_bf16_f32 v229, v86, v87
	global_store_dwordx4 v[238:239], v[226:229], off
	v_mul_f32_e32 v72, v72, v174
	v_mul_f32_e32 v73, v73, v174
	v_mul_f32_e32 v74, v74, v174
	v_mul_f32_e32 v75, v75, v174
	v_mul_f32_e32 v64, v64, v174
	v_mul_f32_e32 v65, v65, v174
	v_mul_f32_e32 v66, v66, v174
	v_mul_f32_e32 v67, v67, v174
	v_mul_f32_e32 v218, 0xbfb8aa3b, v72
; __device__ __forceinline__ unsigned cvt_pk_bf16(float lo, float hi) { unsigned r; asm volatile("v_cvt_pk_bf16_f32 %0, %1, %2" : "=v"(r) : "v"(lo), "v"(hi)); return r; }
;     __device__ __forceinline__ void operator()(const f32x4 (&acc)[2][2][4][2], const Unit& u, int wr, int wc, int fr, int fq) const {
;     ...
;                     for (int e = 0; e < 4; ++e) { const float gt = acc[ai][0][m][n][e] * rs, up = acc[ai][1][m][n][e] * rs;
;                         hv[n * 4 + e] = gt * __builtin_amdgcn_rcpf(1.f + __builtin_amdgcn_exp2f(-1.4426950408889634f * gt)) * up; }
;                 u32x4 w; w.x = cvt_pk_bf16(hv[0], hv[1]); w.y = cvt_pk_bf16(hv[2], hv[3]); w.z = cvt_pk_bf16(hv[4], hv[5]); w.w = cvt_pk_bf16(hv[6], hv[7]);
;                 *(u32x4*)(H + (size_t)row * 2816 + col0) = w;
	v_mul_f32_e32 v219, 0xbfb8aa3b, v73
	v_mul_f32_e32 v220, 0xbfb8aa3b, v74
	v_mul_f32_e32 v221, 0xbfb8aa3b, v75
	v_mul_f32_e32 v222, 0xbfb8aa3b, v64
	v_mul_f32_e32 v223, 0xbfb8aa3b, v65
	v_mul_f32_e32 v224, 0xbfb8aa3b, v66
	v_mul_f32_e32 v225, 0xbfb8aa3b, v67
	v_exp_f32_e32 v218, v218
	v_exp_f32_e32 v219, v219
	v_exp_f32_e32 v220, v220
	v_exp_f32_e32 v221, v221
	v_exp_f32_e32 v222, v222
	v_exp_f32_e32 v223, v223
	v_exp_f32_e32 v224, v224
	v_exp_f32_e32 v225, v225
	v_add_f32_e32 v218, 1.0, v218
	v_add_f32_e32 v219, 1.0, v219
	v_add_f32_e32 v220, 1.0, v220
	v_add_f32_e32 v221, 1.0, v221
	v_add_f32_e32 v222, 1.0, v222
	v_add_f32_e32 v223, 1.0, v223
	v_add_f32_e32 v224, 1.0, v224
	v_add_f32_e32 v225, 1.0, v225
	v_rcp_f32_e32 v218, v218
	v_rcp_f32_e32 v219, v219
	v_rcp_f32_e32 v220, v220
	v_rcp_f32_e32 v221, v221
	v_rcp_f32_e32 v222, v222
	v_rcp_f32_e32 v223, v223
	v_rcp_f32_e32 v224, v224
	v_rcp_f32_e32 v225, v225
	v_mul_f32_e32 v218, v72, v218
	v_mul_f32_e32 v219, v73, v219
	v_mul_f32_e32 v220, v74, v220
	v_mul_f32_e32 v221, v75, v221
	v_mul_f32_e32 v222, v64, v222
	v_mul_f32_e32 v223, v65, v223
	v_mul_f32_e32 v224, v66, v224
	v_mul_f32_e32 v225, v67, v225
	v_mul_f32_e32 v76, v76, v174
	v_mul_f32_e32 v77, v77, v174
	v_mul_f32_e32 v78, v78, v174
	v_mul_f32_e32 v79, v79, v174
	v_mul_f32_e32 v68, v68, v174
	v_mul_f32_e32 v69, v69, v174
	v_mul_f32_e32 v70, v70, v174
	v_mul_f32_e32 v71, v71, v174
	v_mul_f32_e32 v76, v76, v218
	v_mul_f32_e32 v77, v77, v219
	v_mul_f32_e32 v78, v78, v220
	v_mul_f32_e32 v79, v79, v221
	v_mul_f32_e32 v68, v68, v222
	v_mul_f32_e32 v69, v69, v223
	v_mul_f32_e32 v70, v70, v224
	v_mul_f32_e32 v71, v71, v225
	v_cvt_pk_bf16_f32 v230, v76, v77
	v_cvt_pk_bf16_f32 v231, v78, v79
	v_cvt_pk_bf16_f32 v232, v68, v69
	v_cvt_pk_bf16_f32 v233, v70, v71
	global_store_dwordx4 v[240:241], v[230:233], off
	v_mul_f32_e32 v56, v56, v178
	v_mul_f32_e32 v57, v57, v178
	v_mul_f32_e32 v58, v58, v178
	v_mul_f32_e32 v59, v59, v178
	v_mul_f32_e32 v48, v48, v178
	v_mul_f32_e32 v49, v49, v178
	v_mul_f32_e32 v50, v50, v178
	v_mul_f32_e32 v51, v51, v178
	v_mul_f32_e32 v218, 0xbfb8aa3b, v56
	v_mul_f32_e32 v219, 0xbfb8aa3b, v57
	v_mul_f32_e32 v220, 0xbfb8aa3b, v58
	v_mul_f32_e32 v221, 0xbfb8aa3b, v59
	v_mul_f32_e32 v222, 0xbfb8aa3b, v48
	v_mul_f32_e32 v223, 0xbfb8aa3b, v49
	v_mul_f32_e32 v224, 0xbfb8aa3b, v50
	v_mul_f32_e32 v225, 0xbfb8aa3b, v51
	v_exp_f32_e32 v218, v218
	v_exp_f32_e32 v219, v219
	v_exp_f32_e32 v220, v220
	v_exp_f32_e32 v221, v221
	v_exp_f32_e32 v222, v222
	v_exp_f32_e32 v223, v223
	v_exp_f32_e32 v224, v224
	v_exp_f32_e32 v225, v225
	v_add_f32_e32 v218, 1.0, v218
	v_add_f32_e32 v219, 1.0, v219
	v_add_f32_e32 v220, 1.0, v220
	v_add_f32_e32 v221, 1.0, v221
	v_add_f32_e32 v222, 1.0, v222
	v_add_f32_e32 v223, 1.0, v223
	v_add_f32_e32 v224, 1.0, v224
	v_add_f32_e32 v225, 1.0, v225
	v_rcp_f32_e32 v218, v218
	v_rcp_f32_e32 v219, v219
	v_rcp_f32_e32 v220, v220
	v_rcp_f32_e32 v221, v221
	v_rcp_f32_e32 v222, v222
	v_rcp_f32_e32 v223, v223
	v_rcp_f32_e32 v224, v224
	v_rcp_f32_e32 v225, v225
	v_mul_f32_e32 v218, v56, v218
	v_mul_f32_e32 v219, v57, v219
	v_mul_f32_e32 v220, v58, v220
	v_mul_f32_e32 v221, v59, v221
	v_mul_f32_e32 v222, v48, v222
	v_mul_f32_e32 v223, v49, v223
	v_mul_f32_e32 v224, v50, v224
	v_mul_f32_e32 v225, v51, v225
	v_mul_f32_e32 v60, v60, v178
	v_mul_f32_e32 v61, v61, v178
	v_mul_f32_e32 v62, v62, v178
	v_mul_f32_e32 v63, v63, v178
	v_mul_f32_e32 v52, v52, v178
	v_mul_f32_e32 v53, v53, v178
	v_mul_f32_e32 v54, v54, v178
	v_mul_f32_e32 v55, v55, v178
	v_mul_f32_e32 v60, v60, v218
	v_mul_f32_e32 v61, v61, v219
	v_mul_f32_e32 v62, v62, v220
	v_mul_f32_e32 v63, v63, v221
	v_mul_f32_e32 v52, v52, v222
	v_mul_f32_e32 v53, v53, v223
	v_mul_f32_e32 v54, v54, v224
	v_mul_f32_e32 v55, v55, v225
	v_cvt_pk_bf16_f32 v226, v60, v61
	v_cvt_pk_bf16_f32 v227, v62, v63
	v_cvt_pk_bf16_f32 v228, v52, v53
	v_cvt_pk_bf16_f32 v229, v54, v55
	v_lshl_add_u64 v[242:243], s[4:5], 3, v[234:235]
	global_store_dwordx4 v[242:243], v[226:229], off
	v_mul_f32_e32 v40, v40, v182
	v_mul_f32_e32 v41, v41, v182
	v_mul_f32_e32 v42, v42, v182
	v_mul_f32_e32 v43, v43, v182
	v_mul_f32_e32 v32, v32, v182
	v_mul_f32_e32 v33, v33, v182
	v_mul_f32_e32 v34, v34, v182
	v_mul_f32_e32 v35, v35, v182
	v_mul_f32_e32 v218, 0xbfb8aa3b, v40
	v_mul_f32_e32 v219, 0xbfb8aa3b, v41
	v_mul_f32_e32 v220, 0xbfb8aa3b, v42
	v_mul_f32_e32 v221, 0xbfb8aa3b, v43
	v_mul_f32_e32 v222, 0xbfb8aa3b, v32
	v_mul_f32_e32 v223, 0xbfb8aa3b, v33
	v_mul_f32_e32 v224, 0xbfb8aa3b, v34
	v_mul_f32_e32 v225, 0xbfb8aa3b, v35
	v_exp_f32_e32 v218, v218
	v_exp_f32_e32 v219, v219
	v_exp_f32_e32 v220, v220
	v_exp_f32_e32 v221, v221
	v_exp_f32_e32 v222, v222
	v_exp_f32_e32 v223, v223
	v_exp_f32_e32 v224, v224
	v_exp_f32_e32 v225, v225
	v_add_f32_e32 v218, 1.0, v218
	v_add_f32_e32 v219, 1.0, v219
	v_add_f32_e32 v220, 1.0, v220
	v_add_f32_e32 v221, 1.0, v221
	v_add_f32_e32 v222, 1.0, v222
	v_add_f32_e32 v223, 1.0, v223
	v_add_f32_e32 v224, 1.0, v224
	v_add_f32_e32 v225, 1.0, v225
	v_rcp_f32_e32 v218, v218
	v_rcp_f32_e32 v219, v219
	v_rcp_f32_e32 v220, v220
	v_rcp_f32_e32 v221, v221
	v_rcp_f32_e32 v222, v222
	v_rcp_f32_e32 v223, v223
	v_rcp_f32_e32 v224, v224
	v_rcp_f32_e32 v225, v225
	v_mul_f32_e32 v218, v40, v218
	v_mul_f32_e32 v219, v41, v219
	v_mul_f32_e32 v220, v42, v220
	v_mul_f32_e32 v221, v43, v221
; __device__ __forceinline__ unsigned cvt_pk_bf16(float lo, float hi) { unsigned r; asm volatile("v_cvt_pk_bf16_f32 %0, %1, %2" : "=v"(r) : "v"(lo), "v"(hi)); return r; }
; #define PG8_BAR __builtin_amdgcn_s_barrier()
;     __device__ __forceinline__ void operator()(const f32x4 (&acc)[2][2][4][2], const Unit& u, int wr, int wc, int fr, int fq) const {
;     ...
;                     for (int e = 0; e < 4; ++e) { const float gt = acc[ai][0][m][n][e] * rs, up = acc[ai][1][m][n][e] * rs;
;                         hv[n * 4 + e] = gt * __builtin_amdgcn_rcpf(1.f + __builtin_amdgcn_exp2f(-1.4426950408889634f * gt)) * up; }
;                 u32x4 w; w.x = cvt_pk_bf16(hv[0], hv[1]); w.y = cvt_pk_bf16(hv[2], hv[3]); w.z = cvt_pk_bf16(hv[4], hv[5]); w.w = cvt_pk_bf16(hv[6], hv[7]);
;                 *(u32x4*)(H + (size_t)row * 2816 + col0) = w;
; template <class Epi, class Sched, bool ALIGN_EPI = false, bool SP2 = false>
; __device__ __forceinline__ void gemm_phase(PG8_LAS unsigned char* lds, const Gemm g, const Sched& S, const Epi& E) {
;     ...
;         if constexpr (ALIGN_EPI) { if (wr == 0) PG8_BAR; }
;         if constexpr (!Epi::AFTER_DRAIN) { E(acc, cur, wr, wc, fr, fq); S.done(cur); }
;         if (!has_next) break;
	v_mul_f32_e32 v222, v32, v222
	v_mul_f32_e32 v223, v33, v223
	v_mul_f32_e32 v224, v34, v224
	v_mul_f32_e32 v225, v35, v225
	v_mul_f32_e32 v44, v44, v182
	v_mul_f32_e32 v45, v45, v182
	v_mul_f32_e32 v46, v46, v182
	v_mul_f32_e32 v47, v47, v182
	v_mul_f32_e32 v36, v36, v182
	v_mul_f32_e32 v37, v37, v182
	v_mul_f32_e32 v38, v38, v182
	v_mul_f32_e32 v39, v39, v182
	v_mul_f32_e32 v44, v44, v218
	v_mul_f32_e32 v45, v45, v219
	v_mul_f32_e32 v46, v46, v220
	v_mul_f32_e32 v47, v47, v221
	v_mul_f32_e32 v36, v36, v222
	v_mul_f32_e32 v37, v37, v223
	v_mul_f32_e32 v38, v38, v224
	v_mul_f32_e32 v39, v39, v225
	v_cvt_pk_bf16_f32 v230, v44, v45
	v_cvt_pk_bf16_f32 v231, v46, v47
	v_cvt_pk_bf16_f32 v232, v36, v37
	v_cvt_pk_bf16_f32 v233, v38, v39
	v_lshl_add_u64 v[242:243], s[4:5], 3, v[236:237]
	global_store_dwordx4 v[242:243], v[230:233], off
	v_mul_f32_e32 v24, v24, v186
	v_mul_f32_e32 v25, v25, v186
	v_mul_f32_e32 v26, v26, v186
	v_mul_f32_e32 v27, v27, v186
	v_mul_f32_e32 v16, v16, v186
	v_mul_f32_e32 v17, v17, v186
	v_mul_f32_e32 v18, v18, v186
	v_mul_f32_e32 v19, v19, v186
	v_mul_f32_e32 v218, 0xbfb8aa3b, v24
	v_mul_f32_e32 v219, 0xbfb8aa3b, v25
	v_mul_f32_e32 v220, 0xbfb8aa3b, v26
	v_mul_f32_e32 v221, 0xbfb8aa3b, v27
	v_mul_f32_e32 v222, 0xbfb8aa3b, v16
	v_mul_f32_e32 v223, 0xbfb8aa3b, v17
	v_mul_f32_e32 v224, 0xbfb8aa3b, v18
	v_mul_f32_e32 v225, 0xbfb8aa3b, v19
	v_exp_f32_e32 v218, v218
	v_exp_f32_e32 v219, v219
	v_exp_f32_e32 v220, v220
	v_exp_f32_e32 v221, v221
	v_exp_f32_e32 v222, v222
	v_exp_f32_e32 v223, v223
	v_exp_f32_e32 v224, v224
	v_exp_f32_e32 v225, v225
	v_add_f32_e32 v218, 1.0, v218
	v_add_f32_e32 v219, 1.0, v219
	v_add_f32_e32 v220, 1.0, v220
	v_add_f32_e32 v221, 1.0, v221
	v_add_f32_e32 v222, 1.0, v222
	v_add_f32_e32 v223, 1.0, v223
	v_add_f32_e32 v224, 1.0, v224
	v_add_f32_e32 v225, 1.0, v225
	v_rcp_f32_e32 v218, v218
	v_rcp_f32_e32 v219, v219
	v_rcp_f32_e32 v220, v220
	v_rcp_f32_e32 v221, v221
	v_rcp_f32_e32 v222, v222
	v_rcp_f32_e32 v223, v223
	v_rcp_f32_e32 v224, v224
	v_rcp_f32_e32 v225, v225
	v_mul_f32_e32 v218, v24, v218
	v_mul_f32_e32 v219, v25, v219
	v_mul_f32_e32 v220, v26, v220
	v_mul_f32_e32 v221, v27, v221
	v_mul_f32_e32 v222, v16, v222
	v_mul_f32_e32 v223, v17, v223
	v_mul_f32_e32 v224, v18, v224
	v_mul_f32_e32 v225, v19, v225
	v_mul_f32_e32 v28, v28, v186
	v_mul_f32_e32 v29, v29, v186
	v_mul_f32_e32 v30, v30, v186
	v_mul_f32_e32 v31, v31, v186
	v_mul_f32_e32 v20, v20, v186
	v_mul_f32_e32 v21, v21, v186
	v_mul_f32_e32 v22, v22, v186
	v_mul_f32_e32 v23, v23, v186
	v_mul_f32_e32 v28, v28, v218
	v_mul_f32_e32 v29, v29, v219
	v_mul_f32_e32 v30, v30, v220
	v_mul_f32_e32 v31, v31, v221
	v_mul_f32_e32 v20, v20, v222
	v_mul_f32_e32 v21, v21, v223
	v_mul_f32_e32 v22, v22, v224
	v_mul_f32_e32 v23, v23, v225
	v_cvt_pk_bf16_f32 v226, v28, v29
	v_cvt_pk_bf16_f32 v227, v30, v31
	v_cvt_pk_bf16_f32 v228, v20, v21
	v_cvt_pk_bf16_f32 v229, v22, v23
	v_lshl_add_u64 v[242:243], s[4:5], 3, v[238:239]
	global_store_dwordx4 v[242:243], v[226:229], off
	v_mul_f32_e32 v8, v8, v190
	v_mul_f32_e32 v9, v9, v190
	v_mul_f32_e32 v10, v10, v190
	v_mul_f32_e32 v11, v11, v190
	v_mul_f32_e32 v4, v4, v190
	v_mul_f32_e32 v5, v5, v190
	v_mul_f32_e32 v6, v6, v190
	v_mul_f32_e32 v7, v7, v190
	v_mul_f32_e32 v218, 0xbfb8aa3b, v8
	v_mul_f32_e32 v219, 0xbfb8aa3b, v9
	v_mul_f32_e32 v220, 0xbfb8aa3b, v10
	v_mul_f32_e32 v221, 0xbfb8aa3b, v11
	v_mul_f32_e32 v222, 0xbfb8aa3b, v4
	v_mul_f32_e32 v223, 0xbfb8aa3b, v5
	v_mul_f32_e32 v224, 0xbfb8aa3b, v6
	v_mul_f32_e32 v225, 0xbfb8aa3b, v7
	v_exp_f32_e32 v218, v218
	v_exp_f32_e32 v219, v219
	v_exp_f32_e32 v220, v220
	v_exp_f32_e32 v221, v221
	v_exp_f32_e32 v222, v222
	v_exp_f32_e32 v223, v223
	v_exp_f32_e32 v224, v224
	v_exp_f32_e32 v225, v225
	v_add_f32_e32 v218, 1.0, v218
	v_add_f32_e32 v219, 1.0, v219
	v_add_f32_e32 v220, 1.0, v220
	v_add_f32_e32 v221, 1.0, v221
	v_add_f32_e32 v222, 1.0, v222
	v_add_f32_e32 v223, 1.0, v223
	v_add_f32_e32 v224, 1.0, v224
	v_add_f32_e32 v225, 1.0, v225
	v_rcp_f32_e32 v218, v218
	v_rcp_f32_e32 v219, v219
	v_rcp_f32_e32 v220, v220
	v_rcp_f32_e32 v221, v221
	v_rcp_f32_e32 v222, v222
	v_rcp_f32_e32 v223, v223
	v_rcp_f32_e32 v224, v224
	v_rcp_f32_e32 v225, v225
	v_mul_f32_e32 v218, v8, v218
	v_mul_f32_e32 v219, v9, v219
	v_mul_f32_e32 v220, v10, v220
	v_mul_f32_e32 v221, v11, v221
	v_mul_f32_e32 v222, v4, v222
	v_mul_f32_e32 v223, v5, v223
	v_mul_f32_e32 v224, v6, v224
	v_mul_f32_e32 v225, v7, v225
	v_mul_f32_e32 v12, v12, v190
	v_mul_f32_e32 v13, v13, v190
	v_mul_f32_e32 v14, v14, v190
	v_mul_f32_e32 v15, v15, v190
	v_mul_f32_e32 v0, v0, v190
	v_mul_f32_e32 v1, v1, v190
	v_mul_f32_e32 v2, v2, v190
	v_mul_f32_e32 v3, v3, v190
	v_mul_f32_e32 v12, v12, v218
	v_mul_f32_e32 v13, v13, v219
	v_mul_f32_e32 v14, v14, v220
	v_mul_f32_e32 v15, v15, v221
	v_mul_f32_e32 v0, v0, v222
	v_mul_f32_e32 v1, v1, v223
	v_mul_f32_e32 v2, v2, v224
	v_mul_f32_e32 v3, v3, v225
	v_cvt_pk_bf16_f32 v230, v12, v13
	v_cvt_pk_bf16_f32 v231, v14, v15
	v_cvt_pk_bf16_f32 v232, v0, v1
	v_cvt_pk_bf16_f32 v233, v2, v3
	v_lshl_add_u64 v[242:243], s[4:5], 3, v[240:241]
	global_store_dwordx4 v[242:243], v[230:233], off
	s_and_b64 vcc, exec, s[38:39]
	s_mov_b64 s[4:5], -1
	s_cbranch_vccnz .LBB0_1159
	s_andn2_b64 vcc, exec, s[44:45]
	s_cbranch_vccnz .LBB0_1158
	s_barrier
	s_branch .LBB0_1158
